# P2 tile loop: key-position load goes to its own register and its wait/convert moves to the LDS commit at the tile end (was waited right after issue at the top of every tile)
# speedup vs baseline: 1.0206x; 1.0051x over previous
.LBB0_257:
	s_cmpk_lg_i32 s9, 0xff00
	s_cselect_b64 s[44:45], -1, 0
	s_cmpk_eq_i32 s9, 0xff00
	s_cbranch_scc1 .LBB0_259
	v_med3_i32 v64, v212, 0, v197
	v_med3_i32 v68, v211, 0, v197
	v_or_b32_e32 v64, s38, v64
	v_or_b32_e32 v66, s38, v68
	v_mad_u64_u32 v[64:65], s[10:11], v64, s28, v[190:191]
	v_mad_u64_u32 v[66:67], s[10:11], v66, s28, v[192:193]
	v_lshlrev_b32_e32 v68, 2, v68
	v_mad_i32_i24 v65, s39, v187, v65
	v_mad_i32_i24 v67, s39, v187, v67
	global_load_dword v244, v68, s[42:43]
	s_nop 0
	global_load_dwordx4 v[160:163], v[64:65], off offset:1024
	global_load_dwordx4 v[168:171], v[64:65], off offset:1152
	global_load_dwordx4 v[164:167], v[66:67], off offset:1280
	global_load_dwordx4 v[172:175], v[66:67], off offset:1408

.LBB0_261:
	v_sub_f32_e32 v72, v217, v214
	v_sub_f32_e32 v73, v113, v214
	v_sub_f32_e32 v74, v114, v214
	v_sub_f32_e32 v75, v115, v214
	v_sub_f32_e32 v76, v116, v214
	v_sub_f32_e32 v77, v117, v214
	v_sub_f32_e32 v78, v118, v214
	v_sub_f32_e32 v79, v119, v214
	v_sub_f32_e32 v105, v120, v214
	v_sub_f32_e32 v106, v121, v214
	v_sub_f32_e32 v107, v122, v214
	v_sub_f32_e32 v108, v123, v214
	v_sub_f32_e32 v109, v124, v214
	v_sub_f32_e32 v110, v125, v214
	v_sub_f32_e32 v111, v126, v214
	v_sub_f32_e32 v113, v127, v214
	v_sub_f32_e32 v120, v225, v215
	v_sub_f32_e32 v121, v226, v215
	v_sub_f32_e32 v122, v227, v215
	v_sub_f32_e32 v123, v228, v215
	v_sub_f32_e32 v124, v229, v215
	v_sub_f32_e32 v125, v230, v215
	v_sub_f32_e32 v126, v231, v215
	v_sub_f32_e32 v127, v232, v215
	v_add_u32_e32 v242, v216, v210
	v_exp_f32_e32 v72, v72
	v_exp_f32_e32 v73, v73
	v_exp_f32_e32 v74, v74
	v_exp_f32_e32 v75, v75
	v_exp_f32_e32 v76, v76
	v_exp_f32_e32 v77, v77
	v_exp_f32_e32 v78, v78
	v_exp_f32_e32 v79, v79
	v_sub_f32_e32 v114, v218, v214
	v_sub_f32_e32 v115, v219, v214
	v_sub_f32_e32 v116, v220, v214
	v_sub_f32_e32 v117, v221, v214
	v_sub_f32_e32 v118, v222, v214
	v_sub_f32_e32 v119, v223, v214
	v_exp_f32_e32 v120, v120
	v_exp_f32_e32 v121, v121
	v_exp_f32_e32 v122, v122
	v_exp_f32_e32 v123, v123
	v_exp_f32_e32 v124, v124
	v_exp_f32_e32 v125, v125
	v_exp_f32_e32 v126, v126
	v_exp_f32_e32 v127, v127
	v_cvt_pk_bf16_f32 v218, v72, v73
	v_cvt_pk_bf16_f32 v219, v74, v75
	v_cvt_pk_bf16_f32 v220, v76, v77
	v_cvt_pk_bf16_f32 v221, v78, v79
	v_cvt_pk_bf16_f32 v222, v120, v121
	v_cvt_pk_bf16_f32 v223, v122, v123
	v_cvt_pk_bf16_f32 v224, v124, v125
	v_cvt_pk_bf16_f32 v225, v126, v127
	ds_read_b128 v[226:229], v242 offset:18432
	ds_read_b128 v[230:233], v242 offset:23040
	v_sub_f32_e32 v80, v80, v215
	v_exp_f32_e32 v216, v80
	v_sub_f32_e32 v80, v83, v215
	v_exp_f32_e32 v83, v80
	v_sub_f32_e32 v80, v86, v215
	v_exp_f32_e32 v86, v80
	v_sub_f32_e32 v80, v88, v215
	v_exp_f32_e32 v88, v80
	v_sub_f32_e32 v80, v90, v215
	v_exp_f32_e32 v90, v80
	v_sub_f32_e32 v80, v92, v215
	v_sub_f32_e32 v82, v82, v215
	v_exp_f32_e32 v92, v80
	v_sub_f32_e32 v80, v94, v215
	v_exp_f32_e32 v105, v105
	v_exp_f32_e32 v106, v106
	v_exp_f32_e32 v107, v107
	v_exp_f32_e32 v108, v108
	v_exp_f32_e32 v109, v109
	v_exp_f32_e32 v110, v110
	v_exp_f32_e32 v111, v111
	v_exp_f32_e32 v113, v113
	v_sub_f32_e32 v217, v104, v214
	v_exp_f32_e32 v104, v82
	s_waitcnt lgkmcnt(1)
	v_mfma_f32_32x32x16_bf16 v[48:63], v[226:229], v[218:221], v[48:63]
	v_exp_f32_e32 v94, v80
	v_sub_f32_e32 v81, v81, v215
	v_sub_f32_e32 v82, v101, v214
	v_exp_f32_e32 v101, v81
	v_sub_f32_e32 v81, v85, v215
	v_sub_f32_e32 v243, v102, v214
	v_exp_f32_e32 v102, v81
	v_mfma_f32_32x32x16_bf16 v[16:31], v[226:229], v[222:225], v[16:31]
	v_cvt_pk_bf16_f32 v226, v105, v106
	v_cvt_pk_bf16_f32 v227, v107, v108
	v_cvt_pk_bf16_f32 v228, v109, v110
	v_cvt_pk_bf16_f32 v229, v111, v113
	v_cvt_pk_bf16_f32 v234, v104, v216
	v_cvt_pk_bf16_f32 v235, v83, v86
	v_cvt_pk_bf16_f32 v236, v88, v90
	s_waitcnt lgkmcnt(0)
	v_mfma_f32_32x32x16_bf16 v[32:47], v[230:233], v[218:221], v[32:47]
	v_cvt_pk_bf16_f32 v237, v92, v94
	ds_read_b128 v[218:221], v242 offset:18464
	v_sub_f32_e32 v81, v87, v215
	v_exp_f32_e32 v80, v217
	v_exp_f32_e32 v217, v81
	v_sub_f32_e32 v81, v89, v215
	v_sub_f32_e32 v112, v112, v214
	v_mfma_f32_32x32x16_bf16 v[0:15], v[230:233], v[222:225], v[0:15]
	ds_read_b128 v[222:225], v242 offset:23072
	v_sub_f32_e32 v103, v103, v214
	v_sub_f32_e32 v84, v84, v215
	v_exp_f32_e32 v114, v114
	v_exp_f32_e32 v115, v115
	v_exp_f32_e32 v116, v116
	v_exp_f32_e32 v117, v117
	s_waitcnt lgkmcnt(1)
	v_mfma_f32_32x32x16_bf16 v[48:63], v[218:221], v[226:229], v[48:63]
	v_exp_f32_e32 v118, v118
	v_exp_f32_e32 v119, v119
	v_exp_f32_e32 v112, v112
	v_exp_f32_e32 v103, v103
	v_exp_f32_e32 v84, v84
	v_sub_f32_e32 v85, v96, v214
	v_sub_f32_e32 v87, v97, v214
	v_mfma_f32_32x32x16_bf16 v[16:31], v[218:221], v[234:237], v[16:31]
	v_exp_f32_e32 v218, v81
	v_sub_f32_e32 v81, v91, v215
	v_exp_f32_e32 v219, v81
	v_sub_f32_e32 v81, v93, v215
	v_exp_f32_e32 v220, v81
	v_sub_f32_e32 v81, v95, v215
	v_exp_f32_e32 v95, v81
	s_waitcnt lgkmcnt(0)
	v_mfma_f32_32x32x16_bf16 v[32:47], v[222:225], v[226:229], v[32:47]
	v_cvt_pk_bf16_f32 v226, v114, v115
	v_cvt_pk_bf16_f32 v227, v116, v117
	v_cvt_pk_bf16_f32 v228, v118, v119
	v_cvt_pk_bf16_f32 v229, v112, v103
	v_cvt_pk_bf16_f32 v230, v84, v101
	v_cvt_pk_bf16_f32 v231, v102, v217
	v_cvt_pk_bf16_f32 v232, v218, v219
	v_cvt_pk_bf16_f32 v233, v220, v95
	ds_read_b128 v[238:241], v242 offset:18496
	v_mfma_f32_32x32x16_bf16 v[0:15], v[222:225], v[234:237], v[0:15]
	ds_read_b128 v[222:225], v242 offset:23104
	v_sub_f32_e32 v89, v99, v214
	v_sub_f32_e32 v91, v98, v214
	v_sub_f32_e32 v93, v100, v214
	v_sub_f32_e32 v64, v64, v215
	v_sub_f32_e32 v65, v65, v215
	v_sub_f32_e32 v66, v66, v215
	s_waitcnt lgkmcnt(1)
	v_mfma_f32_32x32x16_bf16 v[48:63], v[238:241], v[226:229], v[48:63]
	v_sub_f32_e32 v67, v67, v215
	v_sub_f32_e32 v68, v68, v215
	v_sub_f32_e32 v69, v69, v215
	v_sub_f32_e32 v70, v70, v215
	v_sub_f32_e32 v71, v71, v215
	v_exp_f32_e32 v82, v82
	v_exp_f32_e32 v81, v243
	v_mfma_f32_32x32x16_bf16 v[16:31], v[238:241], v[230:233], v[16:31]
	v_exp_f32_e32 v85, v85
	v_exp_f32_e32 v87, v87
	v_exp_f32_e32 v89, v89
	v_exp_f32_e32 v91, v91
	v_exp_f32_e32 v93, v93
	v_exp_f32_e32 v64, v64
	v_exp_f32_e32 v65, v65
	s_waitcnt lgkmcnt(0)
	v_mfma_f32_32x32x16_bf16 v[32:47], v[222:225], v[226:229], v[32:47]
	v_exp_f32_e32 v66, v66
	v_exp_f32_e32 v67, v67
	v_exp_f32_e32 v68, v68
	v_exp_f32_e32 v69, v69
	v_exp_f32_e32 v70, v70
	v_exp_f32_e32 v71, v71
	v_cvt_pk_bf16_f32 v96, v80, v82
	v_mfma_f32_32x32x16_bf16 v[0:15], v[222:225], v[230:233], v[0:15]
	v_cvt_pk_bf16_f32 v97, v81, v85
	v_cvt_pk_bf16_f32 v98, v87, v89
	v_cvt_pk_bf16_f32 v99, v91, v93
	v_cvt_pk_bf16_f32 v222, v64, v65
	v_cvt_pk_bf16_f32 v223, v66, v67
	v_cvt_pk_bf16_f32 v224, v68, v69
	v_cvt_pk_bf16_f32 v225, v70, v71
	ds_read_b128 v[226:229], v242 offset:18528
	ds_read_b128 v[230:233], v242 offset:23136
	s_waitcnt lgkmcnt(1)
	v_mfma_f32_32x32x16_bf16 v[48:63], v[226:229], v[96:99], v[48:63]
	s_andn2_b64 vcc, exec, s[44:45]
	v_mfma_f32_32x32x16_bf16 v[16:31], v[226:229], v[222:225], v[16:31]
	s_waitcnt lgkmcnt(0)
	v_mfma_f32_32x32x16_bf16 v[32:47], v[230:233], v[96:99], v[32:47]
	v_mfma_f32_32x32x16_bf16 v[0:15], v[230:233], v[222:225], v[0:15]
	s_cbranch_vccnz .LBB0_256
	s_xor_b32 s10, s10, 1
	s_mul_i32 s10, s10, 0x9100
	s_add_i32 s10, s10, 0
	v_add_u32_e32 v96, s10, v204
	v_add3_u32 v97, s10, v205, v206
	s_waitcnt vmcnt(3)
	v_cvt_f32_i32_e32 v213, v244
	ds_write_b128 v96, v[160:163]
	s_waitcnt vmcnt(1)
	ds_write_b16 v97, v164 offset:18432
	ds_write_b16_d16_hi v97, v164 offset:18576
	ds_write_b16 v97, v165 offset:18720
	ds_write_b16_d16_hi v97, v165 offset:18864
	ds_write_b16 v97, v166 offset:19008
	ds_write_b16_d16_hi v97, v166 offset:19152
	ds_write_b16 v97, v167 offset:19296
	ds_write_b16_d16_hi v97, v167 offset:19440
	ds_write_b128 v96, v[168:171] offset:9216
	s_waitcnt vmcnt(0)
	ds_write_b16 v97, v172 offset:27648
	ds_write_b16_d16_hi v97, v172 offset:27792
	ds_write_b16 v97, v173 offset:27936
	ds_write_b16_d16_hi v97, v173 offset:28080
	ds_write_b16 v97, v174 offset:28224
	ds_write_b16_d16_hi v97, v174 offset:28368
	ds_write_b16 v97, v175 offset:28512
	ds_write_b16_d16_hi v97, v175 offset:28656
	v_lshl_add_u32 v96, v199, 2, s10
	ds_write_b32 v96, v213 offset:36864
	s_branch .LBB0_256
